# attention prologue: first item's V^T staging writes deferred behind the second item's loads (one global round trip less)
# speedup vs baseline: 1.0000x; 1.0000x over previous
.LBB0_321:
	v_mov_b32_e32 v82, v1
	s_ashr_i32 s2, s0, 6
	v_ashrrev_i32_e32 v10, 6, v82
	s_lshl_b32 s3, s0, 1
	s_and_b32 s3, s3, 14
	v_ashrrev_i32_e32 v86, 8, v82
	v_lshlrev_b32_e32 v2, 4, v10
	s_lshl_b32 s12, s2, 10
	s_lshl_b32 s2, s2, 4
	v_and_b32_e32 v84, 15, v82
	s_bfe_u32 s8, s0, 0x30003
	v_add_u32_e32 v11, s3, v86
	v_and_b32_e32 v85, 48, v2
	s_add_i32 s9, s12, 0x1000
	s_add_i32 s2, s2, s1
	v_or_b32_e32 v87, v85, v84
	v_lshl_add_u32 v2, v11, 6, s9
	s_lshl_b32 s3, s0, 4
	s_or_b32 s2, s2, s8
	v_or_b32_e32 v131, v2, v87
	s_and_b32 s11, s3, 0xffffff00
	s_ashr_i32 s3, s2, 31
	v_ashrrev_i32_e32 v2, 3, v82
	s_bfe_u32 s13, s0, 0x30001
	s_lshl_b64 s[2:3], s[2:3], 15
	v_readlane_b32 s68, v254, 44
	v_xor_b32_e32 v3, v2, v82
	v_readlane_b32 s69, v254, 45
	s_add_u32 s6, s68, s2
	v_lshlrev_b32_e32 v3, 4, v3
	s_waitcnt vmcnt(28)
	v_lshlrev_b32_e32 v24, 4, v82
	s_addc_u32 s7, s69, s3
	v_and_b32_e32 v162, 0x70, v3
	v_add_u32_e32 v8, 0, v24
	v_ashrrev_i32_e32 v3, 31, v2
	v_lshl_add_u64 v[4:5], s[6:7], 0, v[162:163]
	v_lshlrev_b64 v[6:7], 7, v[2:3]
	v_readfirstlane_b32 s6, v8
	v_add_u32_e32 v9, 0x2000, v8
	v_lshl_add_u64 v[4:5], v[4:5], 0, v[6:7]
	s_mov_b32 m0, s6
	v_readfirstlane_b32 s6, v9
	s_barrier
	global_load_lds_dwordx4 v[4:5], off
	v_lshl_add_u64 v[6:7], v[4:5], 0, s[34:35]
	s_mov_b32 m0, s6
	s_mov_b64 s[6:7], 0x4000
	v_add_u32_e32 v9, 0x4000, v8
	global_load_lds_dwordx4 v[6:7], off
	v_lshl_add_u64 v[6:7], v[4:5], 0, s[6:7]
	v_readfirstlane_b32 s6, v9
	s_mov_b32 m0, s6
	s_mov_b64 s[6:7], 0x6000
	global_load_lds_dwordx4 v[6:7], off
	v_add_u32_e32 v6, 0x6000, v8
	v_readlane_b32 s70, v254, 46
	v_lshl_add_u64 v[4:5], v[4:5], 0, s[6:7]
	v_readfirstlane_b32 s6, v6
	v_readlane_b32 s71, v254, 47
	s_add_u32 s2, s70, s2
	s_mov_b32 m0, s6
	s_addc_u32 s3, s71, s3
	global_load_lds_dwordx4 v[4:5], off
	v_and_b32_e32 v88, 7, v82
	v_lshlrev_b64 v[4:5], 9, v[2:3]
	v_lshl_add_u64 v[6:7], s[2:3], 0, v[4:5]
	v_lshlrev_b32_e32 v4, 6, v88
	v_mov_b32_e32 v5, v163
	v_lshl_add_u64 v[20:21], v[6:7], 0, v[4:5]
	global_load_dwordx4 v[236:239], v[20:21], off offset:48
	global_load_dwordx4 v[240:243], v[20:21], off offset:32
	global_load_dwordx4 v[244:247], v[20:21], off offset:16
	s_nop 0
	global_load_dwordx4 v[248:251], v[20:21], off
	s_movk_i32 s2, 0x210
	v_mul_lo_u32 v5, v2, s2
	s_lshl_b32 s10, s13, 6
	s_lshl_b32 s2, s13, 7
	s_add_u32 s6, s14, s2
	v_add3_u32 v25, 0, v5, v4
	s_addc_u32 s7, s15, 0
	s_lshl_b32 s2, s13, 20
	s_add_u32 s2, s50, s2
	s_addc_u32 s3, s51, 0
	s_lshl_b32 s48, s8, 7
	v_readlane_b32 s72, v254, 48
	v_readlane_b32 s73, v254, 49
	v_readlane_b32 s74, v254, 50
	v_readlane_b32 s75, v254, 51
	v_readlane_b32 s76, v254, 52
	v_readlane_b32 s77, v254, 53
	v_readlane_b32 s78, v254, 54
	v_readlane_b32 s79, v254, 55
	v_readlane_b32 s80, v254, 56
	v_readlane_b32 s81, v254, 57
	v_readlane_b32 s82, v254, 58
	v_readlane_b32 s83, v254, 59
	v_add_u32_e32 v12, s11, v2
	v_lshl_add_u64 v[6:7], s[6:7], 0, v[162:163]
	v_readlane_b32 s6, v253, 60
	v_lshlrev_b64 v[2:3], 6, v[2:3]
	s_nop 0
	v_add_u32_e32 v13, s6, v24
	v_mad_i64_i32 v[8:9], s[6:7], v12, s23, v[6:7]
	v_readfirstlane_b32 s6, v13
	s_mov_b32 m0, s6
	v_add_u32_e32 v14, 0x2000, v13
	global_load_lds_dwordx4 v[8:9], off
	v_add_u32_e32 v8, 64, v12
	v_mad_i64_i32 v[8:9], s[6:7], v8, s23, v[6:7]
	v_readfirstlane_b32 s6, v14
	s_mov_b32 m0, s6
	v_add_u32_e32 v14, 0x4000, v13
	global_load_lds_dwordx4 v[8:9], off
	v_add_u32_e32 v8, 0x80, v12
	v_mad_i64_i32 v[8:9], s[6:7], v8, s23, v[6:7]
	v_readfirstlane_b32 s6, v14
	s_mov_b32 m0, s6
	s_nop 0
	global_load_lds_dwordx4 v[8:9], off
	v_add_u32_e32 v8, 0xc0, v12
	v_mad_i64_i32 v[6:7], s[6:7], v8, s23, v[6:7]
	v_add_u32_e32 v8, 0x6000, v13
	s_nop 0
	v_readfirstlane_b32 s6, v8
	s_mov_b32 m0, s6
	s_ashr_i32 s6, s11, 5
	global_load_lds_dwordx4 v[6:7], off
	v_or_b32_e32 v6, s6, v88
	v_ashrrev_i32_e32 v7, 31, v6
	v_lshlrev_b64 v[6:7], 12, v[6:7]
	v_lshl_add_u64 v[6:7], s[2:3], 0, v[6:7]
	v_lshl_add_u64 v[16:17], v[6:7], 0, v[2:3]
	v_readlane_b32 s2, v253, 61
	s_lshl_b32 s6, s8, 6
	s_nop 0
	v_add3_u32 v20, s2, v5, v4
	global_load_dwordx4 v[2:5], v[16:17], off offset:48
	global_load_dwordx4 v[6:9], v[16:17], off offset:32
	global_load_dwordx4 v[12:15], v[16:17], off offset:16
	s_nop 0
	global_load_dwordx4 v[16:19], v[16:17], off
	s_waitcnt vmcnt(0)
	ds_write_b128 v25, v[248:251] offset:32768
	ds_write_b128 v25, v[244:247] offset:32784
	ds_write_b128 v25, v[240:243] offset:32800
	ds_write_b128 v25, v[236:239] offset:32816
	ds_write_b128 v20, v[16:19]
	ds_write_b128 v20, v[12:15] offset:16
	ds_write_b128 v20, v[6:9] offset:32
	ds_write_b128 v20, v[2:5] offset:48
	v_mov_b64_e32 v[2:3], s[4:5]
	v_lshrrev_b32_e32 v4, 1, v82
	v_mad_i64_i32 v[2:3], s[2:3], v131, s23, v[2:3]
	v_and_b32_e32 v4, 24, v4
	v_lshl_add_u64 v[2:3], v[2:3], 0, s[48:49]
	v_lshlrev_b32_e32 v162, 1, v4
	v_lshl_add_u64 v[6:7], v[2:3], 0, v[162:163]
	global_load_dwordx4 v[2:5], v[6:7], off offset:3072
	s_nop 0
	global_load_dwordx4 v[6:9], v[6:7], off offset:3136
	s_movk_i32 s2, 0x1d1
	v_cmp_gt_i32_e32 vcc, s2, v82
	s_and_saveexec_b64 s[2:3], vcc
	s_cbranch_execz .LBB0_323
	s_or_b32 s7, s8, s1
	v_readlane_b32 s68, v254, 36
	s_mul_hi_i32 s11, s7, 0x744
	s_mulk_i32 s7, 0x744
	v_readlane_b32 s74, v254, 42
	v_readlane_b32 s75, v254, 43
	s_add_u32 s16, s74, s7
	s_addc_u32 s17, s75, s11
	v_ashrrev_i32_e32 v83, 31, v82
	v_lshl_add_u64 v[12:13], v[82:83], 2, s[16:17]
	global_load_dword v12, v[12:13], off
	v_lshl_add_u32 v13, v82, 2, 0
	v_add_u32_e32 v13, 0x20800, v13
	v_readlane_b32 s69, v254, 37
	v_readlane_b32 s70, v254, 38
	v_readlane_b32 s71, v254, 39
	v_readlane_b32 s72, v254, 40
	v_readlane_b32 s73, v254, 41
	s_waitcnt vmcnt(0)
	ds_write_b32 v13, v12
